# baseline (speedup 1.0000x reference)
.LBB0_897:
	s_and_b32 s28, s26, 0x10000
	s_xor_b32 s29, s28, 0x10000
	s_add_u32 m0, s29, s57
	s_add_u32 m0, m0, 0x1000
	v_or_b32_e32 v0, s28, v180
	v_add_u32_e32 v218, v0, v184
	v_add_u32_e32 v0, v0, v183
	s_waitcnt lgkmcnt(2)
	v_mfma_f32_16x16x32_bf16 v[158:161], v[2:5], v[202:205], v[158:161]
	global_load_lds_dwordx4 v166, s[60:61]
	s_add_u32 m0, m0, 0x400
	v_add_u32_e32 v218, v218, v181
	s_add_i32 s27, s27, -1
	v_mfma_f32_16x16x32_bf16 v[154:157], v[6:9], v[202:205], v[154:157]
	s_add_i32 s26, s26, 0x10000
	v_mfma_f32_16x16x32_bf16 v[150:153], v[10:13], v[202:205], v[150:153]
	global_load_lds_dwordx4 v167, s[60:61]
	s_add_u32 m0, m0, 0x400
	v_mfma_f32_16x16x32_bf16 v[146:149], v[14:17], v[202:205], v[146:149]
	ds_read_b128 v[202:205], v0 offset:6144
	s_waitcnt lgkmcnt(2)
	v_mfma_f32_16x16x32_bf16 v[142:145], v[2:5], v[206:209], v[142:145]
	global_load_lds_dwordx4 v168, s[60:61]
	s_add_u32 m0, m0, 0x400
	v_mfma_f32_16x16x32_bf16 v[138:141], v[6:9], v[206:209], v[138:141]
	v_mfma_f32_16x16x32_bf16 v[134:137], v[10:13], v[206:209], v[134:137]
	global_load_lds_dwordx4 v169, s[60:61]
	s_add_u32 s60, s60, 0x80
	s_addc_u32 s61, s61, 0
	v_mfma_f32_16x16x32_bf16 v[130:133], v[14:17], v[206:209], v[130:133]
	ds_read_b128 v[206:209], v0 offset:8192
	s_waitcnt lgkmcnt(2)
	v_mfma_f32_16x16x32_bf16 v[126:129], v[2:5], v[226:229], v[126:129]
	v_mfma_f32_16x16x32_bf16 v[122:125], v[6:9], v[226:229], v[122:125]
	v_mfma_f32_16x16x32_bf16 v[118:121], v[10:13], v[226:229], v[118:121]
	v_mfma_f32_16x16x32_bf16 v[114:117], v[14:17], v[226:229], v[114:117]
	ds_read_b128 v[226:229], v0 offset:10240
	s_waitcnt lgkmcnt(2)
	v_mfma_f32_16x16x32_bf16 v[106:109], v[2:5], v[202:205], v[106:109]
	v_mfma_f32_16x16x32_bf16 v[102:105], v[6:9], v[202:205], v[102:105]
	v_mfma_f32_16x16x32_bf16 v[98:101], v[10:13], v[202:205], v[98:101]
	v_mfma_f32_16x16x32_bf16 v[94:97], v[14:17], v[202:205], v[94:97]
	ds_read_b128 v[202:205], v0 offset:12288
	ds_read_b128 v[230:233], v218 offset:32768
	s_waitcnt lgkmcnt(3)
	v_mfma_f32_16x16x32_bf16 v[86:89], v[2:5], v[206:209], v[86:89]
	v_mfma_f32_16x16x32_bf16 v[82:85], v[6:9], v[206:209], v[82:85]
	v_mfma_f32_16x16x32_bf16 v[78:81], v[10:13], v[206:209], v[78:81]
	v_mfma_f32_16x16x32_bf16 v[74:77], v[14:17], v[206:209], v[74:77]
	ds_read_b128 v[206:209], v0 offset:14336
	ds_read_b128 v[234:237], v218 offset:34816
	v_add_u32_e32 v0, v0, v181
	s_waitcnt lgkmcnt(4)
	v_mfma_f32_16x16x32_bf16 v[70:73], v[2:5], v[226:229], v[70:73]
	v_mfma_f32_16x16x32_bf16 v[66:69], v[6:9], v[226:229], v[66:69]
	v_mfma_f32_16x16x32_bf16 v[62:65], v[10:13], v[226:229], v[62:65]
	v_mfma_f32_16x16x32_bf16 v[58:61], v[14:17], v[226:229], v[58:61]
	ds_read_b128 v[226:229], v0 offset:0
	ds_read_b128 v[238:241], v218 offset:36864
	s_waitcnt lgkmcnt(5)
	v_mfma_f32_16x16x32_bf16 v[54:57], v[2:5], v[202:205], v[54:57]
	v_mfma_f32_16x16x32_bf16 v[50:53], v[6:9], v[202:205], v[50:53]
	v_mfma_f32_16x16x32_bf16 v[46:49], v[10:13], v[202:205], v[46:49]
	v_mfma_f32_16x16x32_bf16 v[42:45], v[14:17], v[202:205], v[42:45]
	ds_read_b128 v[202:205], v0 offset:2048
	ds_read_b128 v[242:245], v218 offset:38912
	s_waitcnt lgkmcnt(5)
	v_mfma_f32_16x16x32_bf16 v[38:41], v[2:5], v[206:209], v[38:41]
	v_mfma_f32_16x16x32_bf16 v[34:37], v[6:9], v[206:209], v[34:37]
	v_mfma_f32_16x16x32_bf16 v[90:93], v[10:13], v[206:209], v[90:93]
	v_mfma_f32_16x16x32_bf16 v[110:113], v[14:17], v[206:209], v[110:113]
	ds_read_b128 v[186:189], v0 offset:4096
	s_waitcnt lgkmcnt(4)
	v_mfma_f32_16x16x32_bf16 v[158:161], v[230:233], v[226:229], v[158:161]
	v_mfma_f32_16x16x32_bf16 v[154:157], v[234:237], v[226:229], v[154:157]
	s_waitcnt lgkmcnt(3)
	v_mfma_f32_16x16x32_bf16 v[150:153], v[238:241], v[226:229], v[150:153]
	s_waitcnt lgkmcnt(1)
	v_mfma_f32_16x16x32_bf16 v[146:149], v[242:245], v[226:229], v[146:149]
	ds_read_b128 v[190:193], v0 offset:6144
	v_mfma_f32_16x16x32_bf16 v[142:145], v[230:233], v[202:205], v[142:145]
	v_mfma_f32_16x16x32_bf16 v[138:141], v[234:237], v[202:205], v[138:141]
	v_mfma_f32_16x16x32_bf16 v[134:137], v[238:241], v[202:205], v[134:137]
	v_mfma_f32_16x16x32_bf16 v[130:133], v[242:245], v[202:205], v[130:133]
	ds_read_b128 v[194:197], v0 offset:8192
	s_waitcnt lgkmcnt(2)
	v_mfma_f32_16x16x32_bf16 v[126:129], v[230:233], v[186:189], v[126:129]
	v_mfma_f32_16x16x32_bf16 v[122:125], v[234:237], v[186:189], v[122:125]
	v_mfma_f32_16x16x32_bf16 v[118:121], v[238:241], v[186:189], v[118:121]
	v_mfma_f32_16x16x32_bf16 v[114:117], v[242:245], v[186:189], v[114:117]
	ds_read_b128 v[186:189], v0 offset:10240
	s_waitcnt lgkmcnt(2)
	v_mfma_f32_16x16x32_bf16 v[106:109], v[230:233], v[190:193], v[106:109]
	v_mfma_f32_16x16x32_bf16 v[102:105], v[234:237], v[190:193], v[102:105]
	v_mfma_f32_16x16x32_bf16 v[98:101], v[238:241], v[190:193], v[98:101]
	v_mfma_f32_16x16x32_bf16 v[94:97], v[242:245], v[190:193], v[94:97]
	ds_read_b128 v[190:193], v0 offset:12288
	s_waitcnt lgkmcnt(2)
	v_mfma_f32_16x16x32_bf16 v[86:89], v[230:233], v[194:197], v[86:89]
	v_mfma_f32_16x16x32_bf16 v[82:85], v[234:237], v[194:197], v[82:85]
	v_mfma_f32_16x16x32_bf16 v[78:81], v[238:241], v[194:197], v[78:81]
	v_mfma_f32_16x16x32_bf16 v[74:77], v[242:245], v[194:197], v[74:77]
	ds_read_b128 v[194:197], v0 offset:14336
	s_waitcnt lgkmcnt(2)
	v_mfma_f32_16x16x32_bf16 v[70:73], v[230:233], v[186:189], v[70:73]
	v_mfma_f32_16x16x32_bf16 v[66:69], v[234:237], v[186:189], v[66:69]
	v_mfma_f32_16x16x32_bf16 v[62:65], v[238:241], v[186:189], v[62:65]
	v_mfma_f32_16x16x32_bf16 v[58:61], v[242:245], v[186:189], v[58:61]
	s_waitcnt lgkmcnt(1)
	v_mfma_f32_16x16x32_bf16 v[54:57], v[230:233], v[190:193], v[54:57]
	v_mfma_f32_16x16x32_bf16 v[50:53], v[234:237], v[190:193], v[50:53]
	v_mfma_f32_16x16x32_bf16 v[46:49], v[238:241], v[190:193], v[46:49]
	v_mfma_f32_16x16x32_bf16 v[42:45], v[242:245], v[190:193], v[42:45]
	s_waitcnt vmcnt(0) lgkmcnt(0)
	s_barrier
; template <int NT, int BM, int BN, bool PLAIN, int NSTAGE, bool EPI_LDS>
; __device__ __forceinline__ void gemm_tile(const Params& p, const GemmDesc& g, bf16_t* lds, const int tid) {
;     ...
;     if (PLAIN) {
;       int kt = 0;
;       for (; kt + 2 < nk; ++kt) {
;         const int cur = kt & 1;
;         COMPUTE_X(cur, 1, 1, kt + 2)
;         __syncthreads();
;       }
;       if (kt + 1 < nk) {
;         const int cur = kt & 1;
;         COMPUTE_X(cur, 1, 0, 0)
;         __syncthreads();
;         ++kt;
;       }
;       {
;         const int cur = kt & 1;
;         COMPUTE_X(cur, 0, 0, 0)
;         __syncthreads();
	s_xor_b32 s29, s28, 0x10000
	v_or_b32_e32 v18, s29, v180
	v_add_u32_e32 v19, v18, v184
	v_add_u32_e32 v18, v18, v183
	ds_read_b128 v[2:5], v19 offset:32768
	ds_read_b128 v[6:9], v19 offset:34816
	ds_read_b128 v[10:13], v19 offset:36864
	ds_read_b128 v[14:17], v19 offset:38912
	ds_read_b128 v[202:205], v18
	ds_read_b128 v[206:209], v18 offset:2048
	ds_read_b128 v[226:229], v18 offset:4096
	s_add_u32 m0, s28, s57
	v_mfma_f32_16x16x32_bf16 v[38:41], v[230:233], v[194:197], v[38:41]
	global_load_lds_dwordx4 v162, s[60:61]
	s_add_u32 m0, m0, 0x400
	v_mfma_f32_16x16x32_bf16 v[34:37], v[234:237], v[194:197], v[34:37]
	global_load_lds_dwordx4 v163, s[60:61]
	s_add_u32 m0, m0, 0x400
	v_mfma_f32_16x16x32_bf16 v[90:93], v[238:241], v[194:197], v[90:93]
	global_load_lds_dwordx4 v164, s[60:61]
	s_add_u32 m0, m0, 0x400
	v_mfma_f32_16x16x32_bf16 v[110:113], v[242:245], v[194:197], v[110:113]
	global_load_lds_dwordx4 v165, s[60:61]
	s_cmp_lg_u32 s27, 0
	s_cbranch_scc1 .LBB0_897
	s_lshl_b32 s3, s3, 16
	s_and_b32 s3, s3, 0x10000
	s_xor_b32 s29, s3, 0x10000
	s_add_u32 m0, s29, s57
	s_add_u32 m0, m0, 0x1000
	s_nop 0
	global_load_lds_dwordx4 v166, s[60:61]
	s_add_u32 m0, m0, 0x400
	s_nop 0
	global_load_lds_dwordx4 v167, s[60:61]
	s_add_u32 m0, m0, 0x400
	s_nop 0
	global_load_lds_dwordx4 v168, s[60:61]
	s_add_u32 m0, m0, 0x400
	s_nop 0
	global_load_lds_dwordx4 v169, s[60:61]
	v_or_b32_e32 v0, s3, v180
	v_add_u32_e32 v198, v0, v184
	ds_read_b128 v[162:165], v198 offset:32768
	ds_read_b128 v[166:169], v198 offset:34816
	ds_read_b128 v[170:173], v198 offset:36864
	ds_read_b128 v[186:189], v198 offset:38912
	v_add_u32_e32 v0, v0, v183
	ds_read_b128 v[174:177], v0
	ds_read_b128 v[190:193], v0 offset:2048
	ds_read_b128 v[194:197], v0 offset:4096
	s_waitcnt lgkmcnt(2)
	v_mfma_f32_16x16x32_bf16 v[30:33], v[162:165], v[174:177], v[158:161]
	s_not_b32 s3, s23
	s_lshl_b32 s3, s3, 16
	s_and_b32 s3, s3, 0x10000
	v_mfma_f32_16x16x32_bf16 v[154:157], v[166:169], v[174:177], v[154:157]
	s_cmp_lg_u32 s56, 9
	s_cselect_b64 s[26:27], -1, 0
	s_mov_b32 s24, s41
	v_mfma_f32_16x16x32_bf16 v[150:153], v[170:173], v[174:177], v[150:153]
	s_mov_b32 s23, s42
	s_mov_b64 s[28:29], -1
	s_and_b64 vcc, exec, s[26:27]
	v_mfma_f32_16x16x32_bf16 v[146:149], v[186:189], v[174:177], v[146:149]
	ds_read_b128 v[158:161], v0 offset:6144
	v_add_u32_e32 v174, v198, v181
	s_waitcnt lgkmcnt(2)
	v_mfma_f32_16x16x32_bf16 v[26:29], v[162:165], v[190:193], v[142:145]
	v_mfma_f32_16x16x32_bf16 v[138:141], v[166:169], v[190:193], v[138:141]
	v_mfma_f32_16x16x32_bf16 v[134:137], v[170:173], v[190:193], v[134:137]
	v_mfma_f32_16x16x32_bf16 v[130:133], v[186:189], v[190:193], v[130:133]
	ds_read_b128 v[142:145], v0 offset:8192
	s_waitcnt lgkmcnt(2)
	v_mfma_f32_16x16x32_bf16 v[22:25], v[162:165], v[194:197], v[126:129]
	v_mfma_f32_16x16x32_bf16 v[122:125], v[166:169], v[194:197], v[122:125]
	v_mfma_f32_16x16x32_bf16 v[118:121], v[170:173], v[194:197], v[118:121]
	v_mfma_f32_16x16x32_bf16 v[114:117], v[186:189], v[194:197], v[114:117]
	ds_read_b128 v[126:129], v0 offset:10240
	s_waitcnt lgkmcnt(2)
	v_mfma_f32_16x16x32_bf16 v[18:21], v[162:165], v[158:161], v[106:109]
	v_mfma_f32_16x16x32_bf16 v[102:105], v[166:169], v[158:161], v[102:105]
	v_mfma_f32_16x16x32_bf16 v[98:101], v[170:173], v[158:161], v[98:101]
	v_mfma_f32_16x16x32_bf16 v[94:97], v[186:189], v[158:161], v[94:97]
	ds_read_b128 v[106:109], v0 offset:12288
	ds_read_b128 v[158:161], v174 offset:32768
	s_waitcnt lgkmcnt(3)
	v_mfma_f32_16x16x32_bf16 v[14:17], v[162:165], v[142:145], v[86:89]
	v_mfma_f32_16x16x32_bf16 v[82:85], v[166:169], v[142:145], v[82:85]
	v_mfma_f32_16x16x32_bf16 v[78:81], v[170:173], v[142:145], v[78:81]
	v_mfma_f32_16x16x32_bf16 v[74:77], v[186:189], v[142:145], v[74:77]
	ds_read_b128 v[86:89], v0 offset:14336
	ds_read_b128 v[142:145], v174 offset:34816
	v_add_u32_e32 v0, v0, v181
	s_waitcnt lgkmcnt(4)
	v_mfma_f32_16x16x32_bf16 v[10:13], v[162:165], v[126:129], v[70:73]
	v_mfma_f32_16x16x32_bf16 v[66:69], v[166:169], v[126:129], v[66:69]
	v_mfma_f32_16x16x32_bf16 v[62:65], v[170:173], v[126:129], v[62:65]
	v_mfma_f32_16x16x32_bf16 v[58:61], v[186:189], v[126:129], v[58:61]
	ds_read_b128 v[70:73], v0 offset:0
	ds_read_b128 v[126:129], v174 offset:36864
	s_waitcnt lgkmcnt(5)
	v_mfma_f32_16x16x32_bf16 v[6:9], v[162:165], v[106:109], v[54:57]
	v_mfma_f32_16x16x32_bf16 v[50:53], v[166:169], v[106:109], v[50:53]
	v_mfma_f32_16x16x32_bf16 v[46:49], v[170:173], v[106:109], v[46:49]
	v_mfma_f32_16x16x32_bf16 v[42:45], v[186:189], v[106:109], v[42:45]
	ds_read_b128 v[106:109], v174 offset:38912
	ds_read_b128 v[54:57], v0 offset:2048
	s_waitcnt lgkmcnt(5)
	v_mfma_f32_16x16x32_bf16 v[2:5], v[162:165], v[86:89], v[38:41]
	v_mfma_f32_16x16x32_bf16 v[34:37], v[166:169], v[86:89], v[34:37]
	v_mfma_f32_16x16x32_bf16 v[38:41], v[170:173], v[86:89], v[90:93]
	v_mfma_f32_16x16x32_bf16 v[86:89], v[186:189], v[86:89], v[110:113]
	s_nop 1
	ds_read_b128 v[90:93], v0 offset:4096
	s_waitcnt lgkmcnt(4)
	v_mfma_f32_16x16x32_bf16 v[30:33], v[158:161], v[70:73], v[30:33]
	v_mfma_f32_16x16x32_bf16 v[110:113], v[142:145], v[70:73], v[154:157]
	s_waitcnt lgkmcnt(3)
	v_mfma_f32_16x16x32_bf16 v[150:153], v[126:129], v[70:73], v[150:153]
	s_waitcnt lgkmcnt(2)
	v_mfma_f32_16x16x32_bf16 v[70:73], v[106:109], v[70:73], v[146:149]
	s_nop 2
	ds_read_b128 v[146:149], v0 offset:6144
	s_waitcnt lgkmcnt(2)
	v_mfma_f32_16x16x32_bf16 v[26:29], v[158:161], v[54:57], v[26:29]
	v_mfma_f32_16x16x32_bf16 v[138:141], v[142:145], v[54:57], v[138:141]
	v_mfma_f32_16x16x32_bf16 v[134:137], v[126:129], v[54:57], v[134:137]
	v_mfma_f32_16x16x32_bf16 v[54:57], v[106:109], v[54:57], v[130:133]
	s_nop 2
	ds_read_b128 v[130:133], v0 offset:8192
	s_waitcnt lgkmcnt(2)
	v_mfma_f32_16x16x32_bf16 v[22:25], v[158:161], v[90:93], v[22:25]
	v_mfma_f32_16x16x32_bf16 v[122:125], v[142:145], v[90:93], v[122:125]
	v_mfma_f32_16x16x32_bf16 v[118:121], v[126:129], v[90:93], v[118:121]
	v_mfma_f32_16x16x32_bf16 v[90:93], v[106:109], v[90:93], v[114:117]
	s_nop 2
	ds_read_b128 v[114:117], v0 offset:10240
	s_waitcnt lgkmcnt(2)
	v_mfma_f32_16x16x32_bf16 v[18:21], v[158:161], v[146:149], v[18:21]
	v_mfma_f32_16x16x32_bf16 v[102:105], v[142:145], v[146:149], v[102:105]
	v_mfma_f32_16x16x32_bf16 v[98:101], v[126:129], v[146:149], v[98:101]
	v_mfma_f32_16x16x32_bf16 v[94:97], v[106:109], v[146:149], v[94:97]
	ds_read_b128 v[146:149], v0 offset:12288
	s_waitcnt lgkmcnt(2)
	v_mfma_f32_16x16x32_bf16 v[14:17], v[158:161], v[130:133], v[14:17]
	v_mfma_f32_16x16x32_bf16 v[82:85], v[142:145], v[130:133], v[82:85]
	v_mfma_f32_16x16x32_bf16 v[78:81], v[126:129], v[130:133], v[78:81]
	v_mfma_f32_16x16x32_bf16 v[74:77], v[106:109], v[130:133], v[74:77]
	ds_read_b128 v[130:133], v0 offset:14336
	v_or_b32_e32 v0, s3, v180
	v_add_u32_e32 v186, v0, v184
	s_waitcnt lgkmcnt(2)
	v_mfma_f32_16x16x32_bf16 v[10:13], v[158:161], v[114:117], v[10:13]
	s_waitcnt vmcnt(0) lgkmcnt(0)
	s_barrier
; template <int NT, int BM, int BN, bool PLAIN, int NSTAGE, bool EPI_LDS>
; __device__ __forceinline__ void gemm_tile(const Params& p, const GemmDesc& g, bf16_t* lds, const int tid) {
;     ...
;   if (EPI_LDS) {
;     constexpr int CST = BN + 16;
;     bf16_t* ct = lds;
;     const bool relu2 = (g.epi == E_RELU2);
; #pragma unroll
;     for (int mi = 0; mi < MI; ++mi)
; #pragma unroll
;       for (int ni = 0; ni < NI; ++ni) {
;         f32x4 v = acc[mi][ni];
;         if (relu2) {
; #pragma unroll
;           for (int j = 0; j < 4; ++j) { const float r = fmaxf(v[j], 0.f); v[j] = r * r; }
;         }
;         u32x2 w;
;         w[0] = pack2(v[0], v[1]);
;         w[1] = pack2(v[2], v[3]);
;         *(u32x2*)(ct + (wm * WTM + mi * 16 + fr) * CST + wn * WTN + ni * 16 + fq * 4) = w;
;       }
	v_mfma_f32_16x16x32_bf16 v[66:69], v[142:145], v[114:117], v[66:69]
	v_add_u32_e32 v0, v0, v183
	v_mfma_f32_16x16x32_bf16 v[62:65], v[126:129], v[114:117], v[62:65]
	v_mfma_f32_16x16x32_bf16 v[58:61], v[106:109], v[114:117], v[58:61]
	v_mfma_f32_16x16x32_bf16 v[6:9], v[158:161], v[146:149], v[6:9]
	v_mfma_f32_16x16x32_bf16 v[50:53], v[142:145], v[146:149], v[50:53]
	v_mfma_f32_16x16x32_bf16 v[46:49], v[126:129], v[146:149], v[46:49]
	v_mfma_f32_16x16x32_bf16 v[42:45], v[106:109], v[146:149], v[42:45]
	v_mfma_f32_16x16x32_bf16 v[2:5], v[158:161], v[130:133], v[2:5]
	v_mfma_f32_16x16x32_bf16 v[34:37], v[142:145], v[130:133], v[34:37]
	v_mfma_f32_16x16x32_bf16 v[38:41], v[126:129], v[130:133], v[38:41]
	v_mfma_f32_16x16x32_bf16 v[86:89], v[106:109], v[130:133], v[86:89]
	ds_read_b128 v[106:109], v186 offset:32768
	ds_read_b128 v[114:117], v186 offset:34816
	ds_read_b128 v[130:133], v186 offset:36864
	ds_read_b128 v[142:145], v186 offset:38912
	ds_read_b128 v[126:129], v0
	ds_read_b128 v[146:149], v0 offset:2048
	ds_read_b128 v[154:157], v0 offset:4096
	s_waitcnt lgkmcnt(2)
	v_mfma_f32_16x16x32_bf16 v[30:33], v[106:109], v[126:129], v[30:33]
	v_mfma_f32_16x16x32_bf16 v[110:113], v[114:117], v[126:129], v[110:113]
	v_mfma_f32_16x16x32_bf16 v[150:153], v[130:133], v[126:129], v[150:153]
	v_mfma_f32_16x16x32_bf16 v[70:73], v[142:145], v[126:129], v[70:73]
	ds_read_b128 v[126:129], v0 offset:6144
	s_waitcnt lgkmcnt(2)
	v_mfma_f32_16x16x32_bf16 v[26:29], v[106:109], v[146:149], v[26:29]
	v_mfma_f32_16x16x32_bf16 v[138:141], v[114:117], v[146:149], v[138:141]
	v_mfma_f32_16x16x32_bf16 v[134:137], v[130:133], v[146:149], v[134:137]
	v_mfma_f32_16x16x32_bf16 v[54:57], v[142:145], v[146:149], v[54:57]
	ds_read_b128 v[146:149], v0 offset:8192
	s_waitcnt lgkmcnt(2)
	v_mfma_f32_16x16x32_bf16 v[22:25], v[106:109], v[154:157], v[22:25]
	v_mfma_f32_16x16x32_bf16 v[158:161], v[114:117], v[154:157], v[122:125]
	v_mfma_f32_16x16x32_bf16 v[162:165], v[130:133], v[154:157], v[118:121]
	v_mfma_f32_16x16x32_bf16 v[154:157], v[142:145], v[154:157], v[90:93]
	s_nop 2
	ds_read_b128 v[90:93], v0 offset:10240
	s_waitcnt lgkmcnt(2)
	v_mfma_f32_16x16x32_bf16 v[18:21], v[106:109], v[126:129], v[18:21]
	v_mfma_f32_16x16x32_bf16 v[166:169], v[114:117], v[126:129], v[102:105]
	v_mfma_f32_16x16x32_bf16 v[170:173], v[130:133], v[126:129], v[98:101]
	v_mfma_f32_16x16x32_bf16 v[174:177], v[142:145], v[126:129], v[94:97]
	s_nop 1
	v_add_u32_e32 v98, v186, v181
	ds_read_b128 v[186:189], v98 offset:32768
	ds_read_b128 v[94:97], v0 offset:12288
	s_waitcnt lgkmcnt(3)
	v_mfma_f32_16x16x32_bf16 v[14:17], v[106:109], v[146:149], v[14:17]
	v_mfma_f32_16x16x32_bf16 v[190:193], v[114:117], v[146:149], v[82:85]
	v_mfma_f32_16x16x32_bf16 v[194:197], v[130:133], v[146:149], v[78:81]
	v_mfma_f32_16x16x32_bf16 v[146:149], v[142:145], v[146:149], v[74:77]
	ds_read_b128 v[198:201], v98 offset:34816
	s_nop 1
	ds_read_b128 v[74:77], v0 offset:14336
	v_add_u32_e32 v0, v0, v181
	s_waitcnt lgkmcnt(4)
	v_mfma_f32_16x16x32_bf16 v[10:13], v[106:109], v[90:93], v[10:13]
	v_mfma_f32_16x16x32_bf16 v[202:205], v[114:117], v[90:93], v[66:69]
	v_mfma_f32_16x16x32_bf16 v[206:209], v[130:133], v[90:93], v[62:65]
	v_mfma_f32_16x16x32_bf16 v[226:229], v[142:145], v[90:93], v[58:61]
	ds_read_b128 v[230:233], v98 offset:36864
	s_nop 1
	ds_read_b128 v[58:61], v0 offset:0
	s_waitcnt lgkmcnt(4)
	v_mfma_f32_16x16x32_bf16 v[6:9], v[106:109], v[94:97], v[6:9]
	v_mfma_f32_16x16x32_bf16 v[234:237], v[114:117], v[94:97], v[50:53]
	v_mfma_f32_16x16x32_bf16 v[238:241], v[130:133], v[94:97], v[46:49]
	v_mfma_f32_16x16x32_bf16 v[242:245], v[142:145], v[94:97], v[42:45]
	ds_read_b128 v[246:249], v98 offset:38912
	s_nop 1
	ds_read_b128 v[42:45], v0 offset:2048
	s_waitcnt lgkmcnt(4)
	v_mfma_f32_16x16x32_bf16 v[2:5], v[106:109], v[74:77], v[2:5]
	v_mfma_f32_16x16x32_bf16 v[218:221], v[114:117], v[74:77], v[34:37]
	v_mfma_f32_16x16x32_bf16 v[130:133], v[130:133], v[74:77], v[38:41]
	v_mfma_f32_16x16x32_bf16 v[142:145], v[142:145], v[74:77], v[86:89]
	s_nop 0
	ds_read_b128 v[34:37], v0 offset:4096
	s_waitcnt lgkmcnt(3)
	v_mfma_f32_16x16x32_bf16 v[126:129], v[186:189], v[58:61], v[30:33]
	v_mfma_f32_16x16x32_bf16 v[122:125], v[198:201], v[58:61], v[110:113]
	v_mfma_f32_16x16x32_bf16 v[118:121], v[230:233], v[58:61], v[150:153]
	s_waitcnt lgkmcnt(2)
	v_mfma_f32_16x16x32_bf16 v[114:117], v[246:249], v[58:61], v[70:73]
	ds_read_b128 v[30:33], v0 offset:6144
	s_waitcnt lgkmcnt(2)
	v_mfma_f32_16x16x32_bf16 v[110:113], v[186:189], v[42:45], v[26:29]
	v_mfma_f32_16x16x32_bf16 v[106:109], v[198:201], v[42:45], v[138:141]
	v_mfma_f32_16x16x32_bf16 v[102:105], v[230:233], v[42:45], v[134:137]
	v_mfma_f32_16x16x32_bf16 v[98:101], v[246:249], v[42:45], v[54:57]
	ds_read_b128 v[26:29], v0 offset:8192
	s_waitcnt lgkmcnt(2)
	v_mfma_f32_16x16x32_bf16 v[94:97], v[186:189], v[34:37], v[22:25]
	v_mfma_f32_16x16x32_bf16 v[90:93], v[198:201], v[34:37], v[158:161]
	v_mfma_f32_16x16x32_bf16 v[86:89], v[230:233], v[34:37], v[162:165]
	v_mfma_f32_16x16x32_bf16 v[82:85], v[246:249], v[34:37], v[154:157]
	ds_read_b128 v[22:25], v0 offset:10240
	s_waitcnt lgkmcnt(2)
	v_mfma_f32_16x16x32_bf16 v[78:81], v[186:189], v[30:33], v[18:21]
	v_mfma_f32_16x16x32_bf16 v[74:77], v[198:201], v[30:33], v[166:169]
	v_mfma_f32_16x16x32_bf16 v[70:73], v[230:233], v[30:33], v[170:173]
	v_mfma_f32_16x16x32_bf16 v[66:69], v[246:249], v[30:33], v[174:177]
	ds_read_b128 v[18:21], v0 offset:12288
	s_waitcnt lgkmcnt(2)
	v_mfma_f32_16x16x32_bf16 v[62:65], v[186:189], v[26:29], v[14:17]
	v_mfma_f32_16x16x32_bf16 v[58:61], v[198:201], v[26:29], v[190:193]
	v_mfma_f32_16x16x32_bf16 v[54:57], v[230:233], v[26:29], v[194:197]
	v_mfma_f32_16x16x32_bf16 v[50:53], v[246:249], v[26:29], v[146:149]
	ds_read_b128 v[134:137], v0 offset:14336
	s_waitcnt lgkmcnt(0)
	s_barrier
	v_mfma_f32_16x16x32_bf16 v[46:49], v[186:189], v[22:25], v[10:13]
	v_mfma_f32_16x16x32_bf16 v[42:45], v[198:201], v[22:25], v[202:205]
	v_mfma_f32_16x16x32_bf16 v[38:41], v[230:233], v[22:25], v[206:209]
	v_mfma_f32_16x16x32_bf16 v[34:37], v[246:249], v[22:25], v[226:229]
	v_mfma_f32_16x16x32_bf16 v[30:33], v[186:189], v[18:21], v[6:9]
	v_mfma_f32_16x16x32_bf16 v[26:29], v[198:201], v[18:21], v[234:237]
	v_mfma_f32_16x16x32_bf16 v[22:25], v[230:233], v[18:21], v[238:241]
	v_mfma_f32_16x16x32_bf16 v[18:21], v[246:249], v[18:21], v[242:245]
	v_mfma_f32_16x16x32_bf16 v[14:17], v[186:189], v[134:137], v[2:5]
	v_mfma_f32_16x16x32_bf16 v[10:13], v[198:201], v[134:137], v[218:221]
	v_mfma_f32_16x16x32_bf16 v[2:5], v[230:233], v[134:137], v[130:133]
	v_mfma_f32_16x16x32_bf16 v[6:9], v[246:249], v[134:137], v[142:145]
	s_cbranch_vccz .LBB0_900
	s_nop 0
	v_cvt_pk_bf16_f32 v130, v126, v127
	v_cvt_pk_bf16_f32 v131, v128, v129
	s_mov_b64 s[28:29], 0
